# attention A/B loop trims (bpermute to rare path, early LDS write, direct reload) + batched gate loads in attention epilogues
# baseline (speedup 1.0000x reference)
; #define LAS __attribute__((address_space(3)))
; DI unsigned cvtpk(float lo, float hi) { f32x2_t v = {lo, hi}; bf16x2_t b = __builtin_convertvector(v, bf16x2_t); return __builtin_bit_cast(unsigned, b); }
; DI float bflo(unsigned w) { return __uint_as_float(w << 16); }
; DI float bfhi(unsigned w) { return __uint_as_float(w & 0xffff0000u); }
; DI float fexp2(float x) { return __builtin_amdgcn_exp2f(x); }
; DI void attn_store(const f32x16 (&o)[2], float inv, bf16_t* d0, int dstride, const bf16_t* g0, int gstride, int lane, LAS unsigned char* stage) {
;     const int r32 = lane & 31, h = lane >> 5;
; #pragma unroll
;     for (int db = 0; db < 2; ++db)
; #pragma unroll
;         for (int g = 0; g < 4; ++g) {
;             const int d = 32 * db + 8 * g + 4 * h;
;             u32x2 w; w.x = cvtpk(o[db][4 * g] * inv, o[db][4 * g + 1] * inv); w.y = cvtpk(o[db][4 * g + 2] * inv, o[db][4 * g + 3] * inv);
;             *(LAS u32x2*)(stage + r32 * 144 + d * 2) = w;
;         }
;     asm volatile("s_waitcnt lgkmcnt(0)" ::: "memory");
;     const int row = lane >> 1, half = lane & 1;
;     u32x4 v[4];
; #pragma unroll
;     for (int i = 0; i < 4; ++i) v[i] = *(const LAS u32x4*)(stage + row * 144 + half * 64 + 16 * i);
;     if (g0) {
;         const bf16_t* gp = g0 + (size_t)row * gstride + half * 32;
; #pragma unroll
;         for (int i = 0; i < 4; ++i) {
;             const u32x4 z = gld16(gp + 8 * i);
; #pragma unroll
;             for (int k = 0; k < 4; ++k) v[i][k] = cvtpk(bflo(v[i][k]) * bflo(z[k]), bfhi(v[i][k]) * bfhi(z[k]));
;         }
;     }
;     bf16_t* dp = d0 + (size_t)row * dstride + half * 32;
; #pragma unroll
;     for (int i = 0; i < 4; ++i) *(u32x4*)(dp + 8 * i) = v[i];
;     asm volatile("s_waitcnt lgkmcnt(0)" ::: "memory");
; }
; DI void phase_attn(int wv, const Params& p, int layer, LAS unsigned char* lds) {
;     ...
;                 const float sink = p.in[10][layer * 4 + qh];
;                 const float lt = lr + fexp2(sink * LOG2E - mr);
;                 attn_store(o, __builtin_amdgcn_rcpf(lt), YG + (2 * Mc + rw0) * 256 + qh * 64, 256, ZS + rw0 * 1024 + 512 + qh * 64, 1024, lane, stage);
.LBB0_1287:
	v_readlane_b32 s12, v255, 48
	s_add_i32 s12, s16, s12
	s_mov_b32 s30, s45
	s_mov_b32 s17, s42
	s_ashr_i32 s13, s12, 31
	v_readlane_b32 s36, v254, 0
	s_lshl_b64 s[12:13], s[12:13], 2
	v_readlane_b32 s40, v254, 4
	v_readlane_b32 s41, v254, 5
	s_add_u32 s12, s40, s12
	s_addc_u32 s13, s41, s13
	global_load_dword v33, v145, s[12:13]
	v_cmp_lt_i32_e32 vcc, v202, v197
	s_mov_b32 s12, 0x3fb8aa3b
	v_lshlrev_b32_e32 v144, 1, v184
	v_cndmask_b32_e32 v32, v185, v202, vcc
	v_lshlrev_b32_e32 v32, 2, v32
	ds_bpermute_b32 v32, v32, v160
	v_readlane_b32 s46, v254, 10
	v_readlane_b32 s47, v254, 11
	v_readlane_b32 s48, v254, 12
	v_readlane_b32 s49, v254, 13
	s_waitcnt lgkmcnt(0)
	v_add_f32_e32 v32, v160, v32
	v_readlane_b32 s39, v254, 3
	v_readlane_b32 s42, v254, 6
	v_readlane_b32 s43, v254, 7
	v_readlane_b32 s44, v254, 8
	v_readlane_b32 s45, v254, 9
	v_readlane_b32 s50, v254, 14
	v_readlane_b32 s51, v254, 15
	v_readlane_b32 s40, v254, 32
	v_readlane_b32 s46, v254, 34
	v_readlane_b32 s48, v255, 3
	v_readlane_b32 s41, v254, 33
	v_readlane_b32 s47, v254, 35
	v_readlane_b32 s43, v255, 2
	v_readlane_b32 s49, v255, 4
	v_readlane_b32 s50, v255, 5
	v_readlane_b32 s51, v255, 6
	s_mov_b32 s39, s91
	s_mov_b32 s42, s17
	s_mov_b32 s45, s30
	s_mov_b32 s91, s1
	v_readlane_b32 s44, v255, 28
	v_readlane_b32 s37, v254, 1
	v_readlane_b32 s38, v254, 2
	s_waitcnt vmcnt(0)
	v_fma_f32 v33, v33, s12, -v137
	v_exp_f32_e32 v33, v33
	v_readlane_b32 s12, v255, 49
	s_add_u32 s14, s12, s26
	v_readlane_b32 s12, v255, 50
	v_add_f32_e32 v32, v32, v33
	v_rcp_f32_e32 v32, v32
	s_addc_u32 s15, s12, s27
	s_lshl_b32 s12, s16, 6
	s_ashr_i32 s13, s12, 31
	s_lshl_b64 s[12:13], s[12:13], 1
	v_pk_mul_f32 v[16:17], v[16:17], v[32:33] op_sel_hi:[1,0]
	v_pk_mul_f32 v[18:19], v[18:19], v[32:33] op_sel_hi:[1,0]
	v_add_u32_e32 v33, v205, v206
	s_add_u32 s26, s14, s12
	v_pk_mul_f32 v[0:1], v[0:1], v[32:33] op_sel_hi:[1,0]
	v_pk_mul_f32 v[2:3], v[2:3], v[32:33] op_sel_hi:[1,0]
	s_addc_u32 s27, s15, s13
	s_lshl_b64 s[14:15], s[4:5], 11
	v_cvt_pk_bf16_f32 v16, v16, v17
	v_cvt_pk_bf16_f32 v17, v18, v19
	v_pk_mul_f32 v[18:19], v[20:21], v[32:33] op_sel_hi:[1,0]
	v_pk_mul_f32 v[20:21], v[22:23], v[32:33] op_sel_hi:[1,0]
	v_cvt_pk_bf16_f32 v0, v0, v1
	v_cvt_pk_bf16_f32 v1, v2, v3
	v_pk_mul_f32 v[2:3], v[4:5], v[32:33] op_sel_hi:[1,0]
	v_pk_mul_f32 v[4:5], v[6:7], v[32:33] op_sel_hi:[1,0]
	s_add_u32 s14, s65, s14
	v_cvt_pk_bf16_f32 v18, v18, v19
	v_cvt_pk_bf16_f32 v19, v20, v21
	v_add_u32_e32 v22, 0xd000, v33
	v_cvt_pk_bf16_f32 v2, v2, v3
	v_cvt_pk_bf16_f32 v3, v4, v5
	s_addc_u32 s15, s74, s15
	ds_write2_b64 v22, v[16:17], v[18:19] offset1:2
	v_pk_mul_f32 v[16:17], v[24:25], v[32:33] op_sel_hi:[1,0]
	v_pk_mul_f32 v[18:19], v[26:27], v[32:33] op_sel_hi:[1,0]
	ds_write2_b64 v22, v[0:1], v[2:3] offset0:8 offset1:10
	v_pk_mul_f32 v[0:1], v[8:9], v[32:33] op_sel_hi:[1,0]
	v_pk_mul_f32 v[2:3], v[10:11], v[32:33] op_sel_hi:[1,0]
	s_add_u32 s28, s14, s12
	v_cvt_pk_bf16_f32 v16, v16, v17
	v_cvt_pk_bf16_f32 v17, v18, v19
	v_pk_mul_f32 v[18:19], v[28:29], v[32:33] op_sel_hi:[1,0]
	v_pk_mul_f32 v[20:21], v[30:31], v[32:33] op_sel_hi:[1,0]
	v_cvt_pk_bf16_f32 v0, v0, v1
	v_cvt_pk_bf16_f32 v1, v2, v3
	v_pk_mul_f32 v[2:3], v[12:13], v[32:33] op_sel_hi:[1,0]
	v_pk_mul_f32 v[4:5], v[14:15], v[32:33] op_sel_hi:[1,0]
	s_addc_u32 s29, s15, s13
	v_cvt_pk_bf16_f32 v18, v18, v19
	v_cvt_pk_bf16_f32 v19, v20, v21
	v_cvt_pk_bf16_f32 v2, v2, v3
	v_cvt_pk_bf16_f32 v3, v4, v5
	ds_write2_b64 v22, v[16:17], v[18:19] offset0:4 offset1:6
	ds_write2_b64 v22, v[0:1], v[2:3] offset0:12 offset1:14
	v_lshl_add_u64 v[16:17], s[28:29], 0, v[144:145]
	v_lshlrev_b32_e32 v144, 1, v180
	s_waitcnt lgkmcnt(0)
	v_add_u32_e32 v4, v207, v208
	v_lshl_add_u64 v[16:17], v[16:17], 0, v[144:145]
	ds_read_b128 v[0:3], v4 offset:53248
	ds_read_b128 v[8:11], v4 offset:53264
	ds_read_b128 v[12:15], v4 offset:53280
	ds_read_b128 v[4:7], v4 offset:53296
	global_load_dwordx4 v[218:221], v[16:17], off offset:1024
	global_load_dwordx4 v[222:225], v[16:17], off offset:1040
	global_load_dwordx4 v[226:229], v[16:17], off offset:1056
	global_load_dwordx4 v[230:233], v[16:17], off offset:1072
	s_waitcnt lgkmcnt(3)
	v_lshlrev_b32_e32 v22, 16, v0
	v_and_b32_e32 v23, 0xffff0000, v0
	s_mov_b64 s[28:29], 0
	s_waitcnt vmcnt(3)
; DI unsigned cvtpk(float lo, float hi) { f32x2_t v = {lo, hi}; bf16x2_t b = __builtin_convertvector(v, bf16x2_t); return __builtin_bit_cast(unsigned, b); }
; DI float bflo(unsigned w) { return __uint_as_float(w << 16); }
; DI float bfhi(unsigned w) { return __uint_as_float(w & 0xffff0000u); }
; DI void attn_store(const f32x16 (&o)[2], float inv, bf16_t* d0, int dstride, const bf16_t* g0, int gstride, int lane, LAS unsigned char* stage) {
;     ...
;     if (g0) {
;         const bf16_t* gp = g0 + (size_t)row * gstride + half * 32;
; #pragma unroll
;         for (int i = 0; i < 4; ++i) {
;             const u32x4 z = gld16(gp + 8 * i);
; #pragma unroll
;             for (int k = 0; k < 4; ++k) v[i][k] = cvtpk(bflo(v[i][k]) * bflo(z[k]), bfhi(v[i][k]) * bfhi(z[k]));
;         }
;     }
;     bf16_t* dp = d0 + (size_t)row * dstride + half * 32;
; #pragma unroll
;     for (int i = 0; i < 4; ++i) *(u32x4*)(dp + 8 * i) = v[i];
;     asm volatile("s_waitcnt lgkmcnt(0)" ::: "memory");
	v_mov_b32_e32 v18, v218
	v_mov_b32_e32 v19, v219
	v_mov_b32_e32 v20, v220
	v_mov_b32_e32 v21, v221
	v_lshlrev_b32_e32 v24, 16, v18
	v_and_b32_e32 v25, 0xffff0000, v18
	v_pk_mul_f32 v[22:23], v[22:23], v[24:25]
	v_lshlrev_b32_e32 v18, 16, v19
	v_cvt_pk_bf16_f32 v0, v22, v23
	v_lshlrev_b32_e32 v22, 16, v1
	v_and_b32_e32 v23, 0xffff0000, v1
	v_and_b32_e32 v19, 0xffff0000, v19
	v_pk_mul_f32 v[18:19], v[22:23], v[18:19]
	v_lshlrev_b32_e32 v22, 16, v20
	v_cvt_pk_bf16_f32 v1, v18, v19
	v_lshlrev_b32_e32 v18, 16, v2
	v_and_b32_e32 v19, 0xffff0000, v2
	v_and_b32_e32 v23, 0xffff0000, v20
	v_pk_mul_f32 v[18:19], v[18:19], v[22:23]
	v_lshlrev_b32_e32 v20, 16, v21
	v_cvt_pk_bf16_f32 v2, v18, v19
	v_lshlrev_b32_e32 v18, 16, v3
	v_and_b32_e32 v19, 0xffff0000, v3
	v_and_b32_e32 v21, 0xffff0000, v21
	v_pk_mul_f32 v[18:19], v[18:19], v[20:21]
	s_waitcnt lgkmcnt(2)
	v_lshlrev_b32_e32 v22, 16, v8
	v_cvt_pk_bf16_f32 v3, v18, v19
	v_and_b32_e32 v23, 0xffff0000, v8
	s_waitcnt vmcnt(2)
	v_mov_b32_e32 v18, v222
	v_mov_b32_e32 v19, v223
	v_mov_b32_e32 v20, v224
	v_mov_b32_e32 v21, v225
	v_lshlrev_b32_e32 v24, 16, v18
	v_and_b32_e32 v25, 0xffff0000, v18
	v_pk_mul_f32 v[22:23], v[22:23], v[24:25]
	v_lshlrev_b32_e32 v18, 16, v19
	v_cvt_pk_bf16_f32 v8, v22, v23
	v_lshlrev_b32_e32 v22, 16, v9
	v_and_b32_e32 v23, 0xffff0000, v9
	v_and_b32_e32 v19, 0xffff0000, v19
	v_pk_mul_f32 v[18:19], v[22:23], v[18:19]
	v_lshlrev_b32_e32 v22, 16, v20
	v_cvt_pk_bf16_f32 v9, v18, v19
	v_lshlrev_b32_e32 v18, 16, v10
	v_and_b32_e32 v19, 0xffff0000, v10
	v_and_b32_e32 v23, 0xffff0000, v20
	v_pk_mul_f32 v[18:19], v[18:19], v[22:23]
	v_lshlrev_b32_e32 v20, 16, v21
	v_cvt_pk_bf16_f32 v10, v18, v19
	v_lshlrev_b32_e32 v18, 16, v11
	v_and_b32_e32 v19, 0xffff0000, v11
	v_and_b32_e32 v21, 0xffff0000, v21
	v_pk_mul_f32 v[18:19], v[18:19], v[20:21]
	s_waitcnt lgkmcnt(1)
	v_lshlrev_b32_e32 v22, 16, v12
	v_cvt_pk_bf16_f32 v11, v18, v19
	v_and_b32_e32 v23, 0xffff0000, v12
	s_waitcnt vmcnt(1)
	v_mov_b32_e32 v18, v226
	v_mov_b32_e32 v19, v227
	v_mov_b32_e32 v20, v228
	v_mov_b32_e32 v21, v229
	v_lshlrev_b32_e32 v24, 16, v18
	v_and_b32_e32 v25, 0xffff0000, v18
	v_pk_mul_f32 v[22:23], v[22:23], v[24:25]
	v_lshlrev_b32_e32 v18, 16, v19
	v_cvt_pk_bf16_f32 v12, v22, v23
	v_lshlrev_b32_e32 v22, 16, v13
	v_and_b32_e32 v23, 0xffff0000, v13
	v_and_b32_e32 v19, 0xffff0000, v19
	v_pk_mul_f32 v[18:19], v[22:23], v[18:19]
	v_lshlrev_b32_e32 v22, 16, v20
	v_cvt_pk_bf16_f32 v13, v18, v19
	v_lshlrev_b32_e32 v18, 16, v14
	v_and_b32_e32 v19, 0xffff0000, v14
	v_and_b32_e32 v23, 0xffff0000, v20
	v_pk_mul_f32 v[18:19], v[18:19], v[22:23]
	v_lshlrev_b32_e32 v20, 16, v21
	v_cvt_pk_bf16_f32 v14, v18, v19
	v_lshlrev_b32_e32 v18, 16, v15
	v_and_b32_e32 v19, 0xffff0000, v15
	v_and_b32_e32 v21, 0xffff0000, v21
	v_pk_mul_f32 v[18:19], v[18:19], v[20:21]
	s_waitcnt lgkmcnt(0)
	v_lshlrev_b32_e32 v20, 16, v4
	v_cvt_pk_bf16_f32 v15, v18, v19
	v_and_b32_e32 v21, 0xffff0000, v4
	s_waitcnt vmcnt(0)
	v_mov_b32_e32 v16, v230
	v_mov_b32_e32 v17, v231
	v_mov_b32_e32 v18, v232
	v_mov_b32_e32 v19, v233
	v_lshlrev_b32_e32 v22, 16, v16
	v_and_b32_e32 v23, 0xffff0000, v16
	v_pk_mul_f32 v[20:21], v[20:21], v[22:23]
	v_lshlrev_b32_e32 v16, 16, v17
	v_cvt_pk_bf16_f32 v4, v20, v21
	v_lshlrev_b32_e32 v20, 16, v5
	v_and_b32_e32 v21, 0xffff0000, v5
	v_and_b32_e32 v17, 0xffff0000, v17
	v_pk_mul_f32 v[16:17], v[20:21], v[16:17]
	v_lshlrev_b32_e32 v20, 16, v18
	v_cvt_pk_bf16_f32 v5, v16, v17
	v_lshlrev_b32_e32 v16, 16, v6
	v_and_b32_e32 v17, 0xffff0000, v6
	v_and_b32_e32 v21, 0xffff0000, v18
	v_pk_mul_f32 v[16:17], v[16:17], v[20:21]
	v_lshlrev_b32_e32 v18, 16, v19
	v_cvt_pk_bf16_f32 v6, v16, v17
	v_lshlrev_b32_e32 v16, 16, v7
	v_and_b32_e32 v17, 0xffff0000, v7
	v_and_b32_e32 v19, 0xffff0000, v19
	v_pk_mul_f32 v[16:17], v[16:17], v[18:19]
	s_nop 0
	v_cvt_pk_bf16_f32 v7, v16, v17
	v_lshlrev_b32_e32 v16, 1, v182
	v_mov_b32_e32 v17, v145
	v_lshl_add_u64 v[16:17], s[26:27], 0, v[16:17]
	v_lshl_add_u64 v[16:17], v[16:17], 0, v[144:145]
	flat_store_dwordx4 v[16:17], v[0:3]
	flat_store_dwordx4 v[16:17], v[8:11] offset:16
	flat_store_dwordx4 v[16:17], v[12:15] offset:32
	flat_store_dwordx4 v[16:17], v[4:7] offset:48
	s_waitcnt lgkmcnt(0)

; #define LAS __attribute__((address_space(3)))
; DI unsigned cvtpk(float lo, float hi) { f32x2_t v = {lo, hi}; bf16x2_t b = __builtin_convertvector(v, bf16x2_t); return __builtin_bit_cast(unsigned, b); }
; DI float fexp2(float x) { return __builtin_amdgcn_exp2f(x); }
; DI float shx(float v, int m) { return __shfl_xor(v, m, 64); }
; #define ATTN_BAR() asm volatile("s_waitcnt lgkmcnt(0)\n\ts_barrier" ::: "memory")
; template <int DQK, bool WIN>
; DI void attn_run(int wv, const bf16_t* Qrow0, int qs, const bf16_t* Kb, int ks, const bf16_t* Vb, int vs,
;                  int kt0, int kt1, int qpos0, int window, LAS unsigned char* lds, f32x16 (&o)[2], float& m_out, float& l_out) {
;     ...
;             for (int r = 0; r < 16; ++r) { p0[r] = fexp2(p0[r]); ls = ls + p0[r]; }
; #pragma unroll
;             for (int r = 0; r < 16; ++r) { p1[r] = fexp2(p1[r]); ls = ls + p1[r]; }
;             lrun = ls;
; #pragma unroll
;             for (int k4 = 0; k4 < 4; ++k4) {
;                 const bf16x8 pf = packp((k4 < 2) ? p0 : p1, k4 & 1);
; #pragma unroll
;                 for (int db = 0; db < 2; ++db) {
;                     const bf16x8 vf = __builtin_shufflevector(vlo[k4][db], vhi[k4][db], 0, 1, 2, 3, 4, 5, 6, 7);
;                     o[db] = __builtin_amdgcn_mfma_f32_32x32x16_bf16(vf, pf, o[db], 0, 0, 0);
;                 }
;             }
;         }
;         if (more) { LAS unsigned char* nb = lds + (buf ^ 1) * BUF;
;             *(LAS u32x4*)(nb + kl0) = rk0; if (k2) *(LAS u32x4*)(nb + kl1) = rk1; *(LAS u32x4*)(nb + vl) = rv; }
;         ATTN_BAR();
;         rk0 = nk0; rk1 = nk1; rv = nv;
;     }
;     m_out = mrun; l_out = lrun + shx(lrun, 32);
; DI void attn_store(const f32x16 (&o)[2], float inv, bf16_t* d0, int dstride, const bf16_t* g0, int gstride, int lane, LAS unsigned char* stage) {
;     const int r32 = lane & 31, h = lane >> 5;
; #pragma unroll
;     for (int db = 0; db < 2; ++db)
; #pragma unroll
;         for (int g = 0; g < 4; ++g) {
;             const int d = 32 * db + 8 * g + 4 * h;
;             u32x2 w; w.x = cvtpk(o[db][4 * g] * inv, o[db][4 * g + 1] * inv); w.y = cvtpk(o[db][4 * g + 2] * inv, o[db][4 * g + 3] * inv);
;             *(LAS u32x2*)(stage + r32 * 144 + d * 2) = w;
;         }
;     asm volatile("s_waitcnt lgkmcnt(0)" ::: "memory");
.LBB0_1299:
	v_exp_f32_e32 v48, v48
	v_exp_f32_e32 v49, v49
	v_exp_f32_e32 v50, v50
	v_exp_f32_e32 v51, v51
	v_exp_f32_e32 v52, v52
	v_exp_f32_e32 v53, v53
	v_exp_f32_e32 v54, v54
	v_exp_f32_e32 v55, v55
	v_exp_f32_e32 v96, v32
	v_exp_f32_e32 v97, v33
	v_exp_f32_e32 v98, v34
	v_exp_f32_e32 v99, v35
	v_cvt_pk_bf16_f32 v32, v48, v49
	v_cvt_pk_bf16_f32 v33, v50, v51
	v_cvt_pk_bf16_f32 v34, v52, v53
	v_cvt_pk_bf16_f32 v35, v54, v55
	v_exp_f32_e32 v56, v56
	v_exp_f32_e32 v57, v57
	v_mfma_f32_32x32x16_bf16 v[16:31], v[92:95], v[32:35], v[16:31]
	v_exp_f32_e32 v58, v58
	v_exp_f32_e32 v59, v59
	v_exp_f32_e32 v60, v60
	v_exp_f32_e32 v61, v61
	v_exp_f32_e32 v62, v62
	v_exp_f32_e32 v63, v63
	v_exp_f32_e32 v36, v36
	v_mfma_f32_32x32x16_bf16 v[0:15], v[88:91], v[32:35], v[0:15]
	v_cvt_pk_bf16_f32 v32, v56, v57
	v_cvt_pk_bf16_f32 v33, v58, v59
	v_cvt_pk_bf16_f32 v34, v60, v61
	v_cvt_pk_bf16_f32 v35, v62, v63
	v_exp_f32_e32 v37, v37
	v_exp_f32_e32 v38, v38
	v_exp_f32_e32 v39, v39
	v_mfma_f32_32x32x16_bf16 v[16:31], v[84:87], v[32:35], v[16:31]
	v_exp_f32_e32 v40, v40
	v_exp_f32_e32 v41, v41
	v_exp_f32_e32 v42, v42
	v_exp_f32_e32 v43, v43
	v_exp_f32_e32 v44, v44
	v_exp_f32_e32 v45, v45
	v_exp_f32_e32 v46, v46
	v_mfma_f32_32x32x16_bf16 v[0:15], v[80:83], v[32:35], v[0:15]
	v_cvt_pk_bf16_f32 v32, v96, v97
	v_cvt_pk_bf16_f32 v33, v98, v99
	v_cvt_pk_bf16_f32 v34, v36, v37
	v_cvt_pk_bf16_f32 v35, v38, v39
	v_exp_f32_e32 v47, v47
	s_add_u32 s12, s4, s10
	s_addc_u32 s13, s5, s11
	v_mfma_f32_32x32x16_bf16 v[16:31], v[68:71], v[32:35], v[16:31]
	s_lshl_b64 s[12:13], s[12:13], 9
	s_add_u32 s14, s52, s12
	s_addc_u32 s15, s53, s13
	s_lshl_b32 s12, s16, 6
	s_ashr_i32 s13, s12, 31
	s_lshl_b64 s[12:13], s[12:13], 1
	s_add_u32 s16, s14, s12
	v_mfma_f32_32x32x16_bf16 v[0:15], v[64:67], v[32:35], v[0:15]
	v_cvt_pk_bf16_f32 v32, v40, v41
	v_cvt_pk_bf16_f32 v33, v42, v43
	v_cvt_pk_bf16_f32 v34, v44, v45
	v_cvt_pk_bf16_f32 v35, v46, v47
	s_addc_u32 s17, s15, s13
	s_lshl_b64 s[4:5], s[4:5], 11
	s_add_u32 s4, s65, s4
	v_mfma_f32_32x32x16_bf16 v[16:31], v[72:75], v[32:35], v[16:31]
	s_waitcnt lgkmcnt(0)
	s_barrier
	s_addc_u32 s5, s74, s5
	s_add_u32 s4, s4, s12
	s_addc_u32 s5, s5, s13
	v_lshlrev_b32_e32 v144, 1, v184
	v_mfma_f32_32x32x16_bf16 v[0:15], v[76:79], v[32:35], v[0:15]
	v_add_f32_e32 v32, v48, v163
	v_add_f32_e32 v32, v49, v32
	v_add_f32_e32 v32, v50, v32
	v_add_f32_e32 v32, v51, v32
	v_add_f32_e32 v32, v52, v32
	v_add_f32_e32 v32, v53, v32
	v_add_f32_e32 v32, v54, v32
	v_add_f32_e32 v32, v55, v32
	v_add_f32_e32 v32, v56, v32
	v_add_f32_e32 v32, v57, v32
	v_add_f32_e32 v32, v58, v32
	v_add_f32_e32 v32, v59, v32
	v_add_f32_e32 v32, v60, v32
	v_add_f32_e32 v32, v61, v32
	v_add_f32_e32 v32, v62, v32
	v_add_f32_e32 v32, v63, v32
	v_add_f32_e32 v32, v96, v32
	v_add_f32_e32 v32, v97, v32
	v_add_f32_e32 v32, v98, v32
	v_add_f32_e32 v32, v99, v32
	v_add_f32_e32 v32, v36, v32
	v_add_f32_e32 v32, v37, v32
	v_add_f32_e32 v32, v38, v32
	v_add_f32_e32 v32, v39, v32
	v_add_f32_e32 v32, v40, v32
	v_add_f32_e32 v32, v41, v32
	v_add_f32_e32 v32, v42, v32
	v_add_f32_e32 v32, v43, v32
	v_add_f32_e32 v32, v44, v32
	v_add_f32_e32 v32, v45, v32
	v_add_f32_e32 v32, v46, v32
	v_add_f32_e32 v32, v47, v32
	ds_bpermute_b32 v33, v165, v32
	s_waitcnt lgkmcnt(0)
	v_add_f32_e32 v32, v32, v33
	v_rcp_f32_e32 v32, v32
	s_nop 0
	v_pk_mul_f32 v[16:17], v[16:17], v[32:33] op_sel_hi:[1,0]
	v_pk_mul_f32 v[18:19], v[18:19], v[32:33] op_sel_hi:[1,0]
	v_add_u32_e32 v33, v205, v206
	v_pk_mul_f32 v[0:1], v[0:1], v[32:33] op_sel_hi:[1,0]
	v_pk_mul_f32 v[2:3], v[2:3], v[32:33] op_sel_hi:[1,0]
	v_cvt_pk_bf16_f32 v16, v16, v17
	v_cvt_pk_bf16_f32 v17, v18, v19
	v_pk_mul_f32 v[18:19], v[20:21], v[32:33] op_sel_hi:[1,0]
	v_pk_mul_f32 v[20:21], v[22:23], v[32:33] op_sel_hi:[1,0]
	v_cvt_pk_bf16_f32 v0, v0, v1
	v_cvt_pk_bf16_f32 v1, v2, v3
	v_pk_mul_f32 v[2:3], v[4:5], v[32:33] op_sel_hi:[1,0]
	v_pk_mul_f32 v[4:5], v[6:7], v[32:33] op_sel_hi:[1,0]
	v_cvt_pk_bf16_f32 v18, v18, v19
	v_cvt_pk_bf16_f32 v19, v20, v21
	v_add_u32_e32 v22, 0xd000, v33
	v_cvt_pk_bf16_f32 v2, v2, v3
	v_cvt_pk_bf16_f32 v3, v4, v5
	ds_write2_b64 v22, v[16:17], v[18:19] offset1:2
	v_pk_mul_f32 v[16:17], v[24:25], v[32:33] op_sel_hi:[1,0]
	v_pk_mul_f32 v[18:19], v[26:27], v[32:33] op_sel_hi:[1,0]
	ds_write2_b64 v22, v[0:1], v[2:3] offset0:8 offset1:10
	v_pk_mul_f32 v[0:1], v[8:9], v[32:33] op_sel_hi:[1,0]
	v_pk_mul_f32 v[2:3], v[10:11], v[32:33] op_sel_hi:[1,0]
	v_cvt_pk_bf16_f32 v16, v16, v17
	v_cvt_pk_bf16_f32 v17, v18, v19
	v_pk_mul_f32 v[18:19], v[28:29], v[32:33] op_sel_hi:[1,0]
	v_pk_mul_f32 v[20:21], v[30:31], v[32:33] op_sel_hi:[1,0]
	v_cvt_pk_bf16_f32 v0, v0, v1
	v_cvt_pk_bf16_f32 v1, v2, v3
	v_pk_mul_f32 v[2:3], v[12:13], v[32:33] op_sel_hi:[1,0]
	v_pk_mul_f32 v[4:5], v[14:15], v[32:33] op_sel_hi:[1,0]
	v_cvt_pk_bf16_f32 v18, v18, v19
	v_cvt_pk_bf16_f32 v19, v20, v21
	v_cvt_pk_bf16_f32 v2, v2, v3
	v_cvt_pk_bf16_f32 v3, v4, v5
	ds_write2_b64 v22, v[16:17], v[18:19] offset0:4 offset1:6
	ds_write2_b64 v22, v[0:1], v[2:3] offset0:12 offset1:14
	v_lshl_add_u64 v[16:17], s[4:5], 0, v[144:145]
	v_lshlrev_b32_e32 v144, 1, v180
	s_waitcnt lgkmcnt(0)
; #define LAS __attribute__((address_space(3)))
; DI unsigned cvtpk(float lo, float hi) { f32x2_t v = {lo, hi}; bf16x2_t b = __builtin_convertvector(v, bf16x2_t); return __builtin_bit_cast(unsigned, b); }
; DI float bflo(unsigned w) { return __uint_as_float(w << 16); }
; DI float bfhi(unsigned w) { return __uint_as_float(w & 0xffff0000u); }
; DI void attn_store(const f32x16 (&o)[2], float inv, bf16_t* d0, int dstride, const bf16_t* g0, int gstride, int lane, LAS unsigned char* stage) {
;     ...
;     const int row = lane >> 1, half = lane & 1;
;     u32x4 v[4];
; #pragma unroll
;     for (int i = 0; i < 4; ++i) v[i] = *(const LAS u32x4*)(stage + row * 144 + half * 64 + 16 * i);
;     if (g0) {
;         const bf16_t* gp = g0 + (size_t)row * gstride + half * 32;
; #pragma unroll
;         for (int i = 0; i < 4; ++i) {
;             const u32x4 z = gld16(gp + 8 * i);
; #pragma unroll
;             for (int k = 0; k < 4; ++k) v[i][k] = cvtpk(bflo(v[i][k]) * bflo(z[k]), bfhi(v[i][k]) * bfhi(z[k]));
;         }
;     }
;     bf16_t* dp = d0 + (size_t)row * dstride + half * 32;
; #pragma unroll
;     for (int i = 0; i < 4; ++i) *(u32x4*)(dp + 8 * i) = v[i];
;     asm volatile("s_waitcnt lgkmcnt(0)" ::: "memory");
	v_add_u32_e32 v0, v207, v208
	v_lshl_add_u64 v[16:17], v[16:17], 0, v[144:145]
	ds_read_b128 v[4:7], v0 offset:53248
	ds_read_b128 v[8:11], v0 offset:53264
	ds_read_b128 v[12:15], v0 offset:53280
	ds_read_b128 v[0:3], v0 offset:53296
	global_load_dwordx4 v[218:221], v[16:17], off offset:512
	global_load_dwordx4 v[222:225], v[16:17], off offset:528
	global_load_dwordx4 v[226:229], v[16:17], off offset:544
	global_load_dwordx4 v[230:233], v[16:17], off offset:560
	s_waitcnt lgkmcnt(3)
	v_lshlrev_b32_e32 v22, 16, v4
	v_and_b32_e32 v23, 0xffff0000, v4
	s_waitcnt vmcnt(3)
	v_mov_b32_e32 v18, v218
	v_mov_b32_e32 v19, v219
	v_mov_b32_e32 v20, v220
	v_mov_b32_e32 v21, v221
	v_lshlrev_b32_e32 v24, 16, v18
	v_and_b32_e32 v25, 0xffff0000, v18
	v_pk_mul_f32 v[22:23], v[22:23], v[24:25]
	v_lshlrev_b32_e32 v18, 16, v19
	v_cvt_pk_bf16_f32 v4, v22, v23
	v_lshlrev_b32_e32 v22, 16, v5
	v_and_b32_e32 v23, 0xffff0000, v5
	v_and_b32_e32 v19, 0xffff0000, v19
	v_pk_mul_f32 v[18:19], v[22:23], v[18:19]
	v_lshlrev_b32_e32 v22, 16, v20
	v_cvt_pk_bf16_f32 v5, v18, v19
	v_lshlrev_b32_e32 v18, 16, v6
	v_and_b32_e32 v19, 0xffff0000, v6
	v_and_b32_e32 v23, 0xffff0000, v20
	v_pk_mul_f32 v[18:19], v[18:19], v[22:23]
	v_lshlrev_b32_e32 v20, 16, v21
	v_cvt_pk_bf16_f32 v6, v18, v19
	v_lshlrev_b32_e32 v18, 16, v7
	v_and_b32_e32 v19, 0xffff0000, v7
	v_and_b32_e32 v21, 0xffff0000, v21
	v_pk_mul_f32 v[18:19], v[18:19], v[20:21]
	s_waitcnt lgkmcnt(2)
	v_lshlrev_b32_e32 v22, 16, v8
	v_cvt_pk_bf16_f32 v7, v18, v19
	v_and_b32_e32 v23, 0xffff0000, v8
	s_waitcnt vmcnt(2)
	v_mov_b32_e32 v18, v222
	v_mov_b32_e32 v19, v223
	v_mov_b32_e32 v20, v224
	v_mov_b32_e32 v21, v225
	v_lshlrev_b32_e32 v24, 16, v18
	v_and_b32_e32 v25, 0xffff0000, v18
	v_pk_mul_f32 v[22:23], v[22:23], v[24:25]
	v_lshlrev_b32_e32 v18, 16, v19
	v_cvt_pk_bf16_f32 v8, v22, v23
	v_lshlrev_b32_e32 v22, 16, v9
	v_and_b32_e32 v23, 0xffff0000, v9
	v_and_b32_e32 v19, 0xffff0000, v19
	v_pk_mul_f32 v[18:19], v[22:23], v[18:19]
	v_lshlrev_b32_e32 v22, 16, v20
	v_cvt_pk_bf16_f32 v9, v18, v19
	v_lshlrev_b32_e32 v18, 16, v10
	v_and_b32_e32 v19, 0xffff0000, v10
	v_and_b32_e32 v23, 0xffff0000, v20
	v_pk_mul_f32 v[18:19], v[18:19], v[22:23]
	v_lshlrev_b32_e32 v20, 16, v21
	v_cvt_pk_bf16_f32 v10, v18, v19
	v_lshlrev_b32_e32 v18, 16, v11
	v_and_b32_e32 v19, 0xffff0000, v11
	v_and_b32_e32 v21, 0xffff0000, v21
	v_pk_mul_f32 v[18:19], v[18:19], v[20:21]
	s_waitcnt lgkmcnt(1)
	v_lshlrev_b32_e32 v22, 16, v12
	v_cvt_pk_bf16_f32 v11, v18, v19
	v_and_b32_e32 v23, 0xffff0000, v12
	s_waitcnt vmcnt(1)
	v_mov_b32_e32 v18, v226
	v_mov_b32_e32 v19, v227
	v_mov_b32_e32 v20, v228
	v_mov_b32_e32 v21, v229
	v_lshlrev_b32_e32 v24, 16, v18
	v_and_b32_e32 v25, 0xffff0000, v18
	v_pk_mul_f32 v[22:23], v[22:23], v[24:25]
	v_lshlrev_b32_e32 v18, 16, v19
	v_cvt_pk_bf16_f32 v12, v22, v23
	v_lshlrev_b32_e32 v22, 16, v13
	v_and_b32_e32 v23, 0xffff0000, v13
	v_and_b32_e32 v19, 0xffff0000, v19
	v_pk_mul_f32 v[18:19], v[22:23], v[18:19]
	v_lshlrev_b32_e32 v22, 16, v20
	v_cvt_pk_bf16_f32 v13, v18, v19
	v_lshlrev_b32_e32 v18, 16, v14
	v_and_b32_e32 v19, 0xffff0000, v14
	v_and_b32_e32 v23, 0xffff0000, v20
	v_pk_mul_f32 v[18:19], v[18:19], v[22:23]
	v_lshlrev_b32_e32 v20, 16, v21
	v_cvt_pk_bf16_f32 v14, v18, v19
	v_lshlrev_b32_e32 v18, 16, v15
	v_and_b32_e32 v19, 0xffff0000, v15
	v_and_b32_e32 v21, 0xffff0000, v21
	v_pk_mul_f32 v[18:19], v[18:19], v[20:21]
	s_waitcnt lgkmcnt(0)
	v_lshlrev_b32_e32 v20, 16, v0
	v_cvt_pk_bf16_f32 v15, v18, v19
	v_and_b32_e32 v21, 0xffff0000, v0
	s_waitcnt vmcnt(0)
	v_mov_b32_e32 v16, v230
	v_mov_b32_e32 v17, v231
	v_mov_b32_e32 v18, v232
	v_mov_b32_e32 v19, v233
	v_lshlrev_b32_e32 v22, 16, v16
	v_and_b32_e32 v23, 0xffff0000, v16
	v_pk_mul_f32 v[20:21], v[20:21], v[22:23]
	v_lshlrev_b32_e32 v16, 16, v17
	v_cvt_pk_bf16_f32 v0, v20, v21
	v_lshlrev_b32_e32 v20, 16, v1
	v_and_b32_e32 v21, 0xffff0000, v1
	v_and_b32_e32 v17, 0xffff0000, v17
	v_pk_mul_f32 v[16:17], v[20:21], v[16:17]
	v_lshlrev_b32_e32 v20, 16, v18
	v_cvt_pk_bf16_f32 v1, v16, v17
	v_lshlrev_b32_e32 v16, 16, v2
	v_and_b32_e32 v17, 0xffff0000, v2
	v_and_b32_e32 v21, 0xffff0000, v18
	v_pk_mul_f32 v[16:17], v[16:17], v[20:21]
	v_lshlrev_b32_e32 v18, 16, v19
	v_cvt_pk_bf16_f32 v2, v16, v17
	v_lshlrev_b32_e32 v16, 16, v3
	v_and_b32_e32 v17, 0xffff0000, v3
	v_and_b32_e32 v19, 0xffff0000, v19
	v_pk_mul_f32 v[16:17], v[16:17], v[18:19]
	s_nop 0
	v_cvt_pk_bf16_f32 v3, v16, v17
	v_lshlrev_b32_e32 v16, 1, v182
	v_mov_b32_e32 v17, v145
	v_lshl_add_u64 v[16:17], s[16:17], 0, v[16:17]
	v_lshl_add_u64 v[16:17], v[16:17], 0, v[144:145]
	flat_store_dwordx4 v[16:17], v[4:7]
	flat_store_dwordx4 v[16:17], v[8:11] offset:16
	flat_store_dwordx4 v[16:17], v[12:15] offset:32
	flat_store_dwordx4 v[16:17], v[0:3] offset:48
	s_waitcnt lgkmcnt(0)
	s_cbranch_execnz .LBB0_1238

; #define LAS __attribute__((address_space(3)))
; DI unsigned cvtpk(float lo, float hi) { f32x2_t v = {lo, hi}; bf16x2_t b = __builtin_convertvector(v, bf16x2_t); return __builtin_bit_cast(unsigned, b); }
; DI float fexp2(float x) { return __builtin_amdgcn_exp2f(x); }
; DI float shx(float v, int m) { return __shfl_xor(v, m, 64); }
; #define ATTN_BAR() asm volatile("s_waitcnt lgkmcnt(0)\n\ts_barrier" ::: "memory")
; template <int DQK, bool WIN>
; DI void attn_run(int wv, const bf16_t* Qrow0, int qs, const bf16_t* Kb, int ks, const bf16_t* Vb, int vs,
;                  int kt0, int kt1, int qpos0, int window, LAS unsigned char* lds, f32x16 (&o)[2], float& m_out, float& l_out) {
;     ...
;             for (int r = 0; r < 16; ++r) { p0[r] = fexp2(p0[r]); ls = ls + p0[r]; }
; #pragma unroll
;             for (int r = 0; r < 16; ++r) { p1[r] = fexp2(p1[r]); ls = ls + p1[r]; }
;             lrun = ls;
; #pragma unroll
;             for (int k4 = 0; k4 < 4; ++k4) {
;                 const bf16x8 pf = packp((k4 < 2) ? p0 : p1, k4 & 1);
; #pragma unroll
;                 for (int db = 0; db < 2; ++db) {
;                     const bf16x8 vf = __builtin_shufflevector(vlo[k4][db], vhi[k4][db], 0, 1, 2, 3, 4, 5, 6, 7);
;                     o[db] = __builtin_amdgcn_mfma_f32_32x32x16_bf16(vf, pf, o[db], 0, 0, 0);
;                 }
;             }
;         }
;         if (more) { LAS unsigned char* nb = lds + (buf ^ 1) * BUF;
;             *(LAS u32x4*)(nb + kl0) = rk0; if (k2) *(LAS u32x4*)(nb + kl1) = rk1; *(LAS u32x4*)(nb + vl) = rv; }
;         ATTN_BAR();
;         rk0 = nk0; rk1 = nk1; rv = nv;
;     }
;     m_out = mrun; l_out = lrun + shx(lrun, 32);
; }
; DI void attn_store(const f32x16 (&o)[2], float inv, bf16_t* d0, int dstride, const bf16_t* g0, int gstride, int lane, LAS unsigned char* stage) {
;     const int r32 = lane & 31, h = lane >> 5;
; #pragma unroll
;     for (int db = 0; db < 2; ++db)
; #pragma unroll
;         for (int g = 0; g < 4; ++g) {
;             const int d = 32 * db + 8 * g + 4 * h;
;             u32x2 w; w.x = cvtpk(o[db][4 * g] * inv, o[db][4 * g + 1] * inv); w.y = cvtpk(o[db][4 * g + 2] * inv, o[db][4 * g + 3] * inv);
;             *(LAS u32x2*)(stage + r32 * 144 + d * 2) = w;
;         }
;     asm volatile("s_waitcnt lgkmcnt(0)" ::: "memory");
.LBB0_1323:
	v_exp_f32_e32 v48, v48
	v_exp_f32_e32 v49, v49
	v_exp_f32_e32 v50, v50
	v_exp_f32_e32 v51, v51
	v_exp_f32_e32 v52, v52
	v_exp_f32_e32 v53, v53
	v_exp_f32_e32 v54, v54
	v_exp_f32_e32 v55, v55
	v_exp_f32_e32 v96, v32
	v_exp_f32_e32 v97, v33
	v_exp_f32_e32 v98, v34
	v_exp_f32_e32 v99, v35
	v_cvt_pk_bf16_f32 v32, v48, v49
	v_cvt_pk_bf16_f32 v33, v50, v51
	v_cvt_pk_bf16_f32 v34, v52, v53
	v_cvt_pk_bf16_f32 v35, v54, v55
	v_exp_f32_e32 v56, v56
	v_exp_f32_e32 v57, v57
	v_mfma_f32_32x32x16_bf16 v[16:31], v[92:95], v[32:35], v[16:31]
	v_exp_f32_e32 v58, v58
	v_exp_f32_e32 v59, v59
	v_exp_f32_e32 v60, v60
	v_exp_f32_e32 v61, v61
	v_exp_f32_e32 v62, v62
	v_exp_f32_e32 v63, v63
	v_exp_f32_e32 v36, v36
	v_mfma_f32_32x32x16_bf16 v[0:15], v[88:91], v[32:35], v[0:15]
	v_cvt_pk_bf16_f32 v32, v56, v57
	v_cvt_pk_bf16_f32 v33, v58, v59
	v_cvt_pk_bf16_f32 v34, v60, v61
	v_cvt_pk_bf16_f32 v35, v62, v63
	v_exp_f32_e32 v37, v37
	v_exp_f32_e32 v38, v38
	v_exp_f32_e32 v39, v39
	v_mfma_f32_32x32x16_bf16 v[16:31], v[84:87], v[32:35], v[16:31]
	v_exp_f32_e32 v40, v40
	v_exp_f32_e32 v41, v41
	v_exp_f32_e32 v42, v42
	v_exp_f32_e32 v43, v43
	v_exp_f32_e32 v44, v44
	v_exp_f32_e32 v45, v45
	v_exp_f32_e32 v46, v46
	v_mfma_f32_32x32x16_bf16 v[0:15], v[80:83], v[32:35], v[0:15]
	v_cvt_pk_bf16_f32 v32, v96, v97
	v_cvt_pk_bf16_f32 v33, v98, v99
	v_cvt_pk_bf16_f32 v34, v36, v37
	v_cvt_pk_bf16_f32 v35, v38, v39
	v_exp_f32_e32 v47, v47
	s_waitcnt lgkmcnt(0)
	s_barrier
	v_readlane_b32 s12, v255, 20
	v_mfma_f32_32x32x16_bf16 v[16:31], v[68:71], v[32:35], v[16:31]
	v_readlane_b32 s13, v255, 21
	s_lshl_b32 s4, s24, 6
	s_andn2_b64 vcc, exec, s[12:13]
	v_mfma_f32_32x32x16_bf16 v[0:15], v[64:67], v[32:35], v[0:15]
	v_cvt_pk_bf16_f32 v32, v40, v41
	v_cvt_pk_bf16_f32 v33, v42, v43
	v_cvt_pk_bf16_f32 v34, v44, v45
	v_cvt_pk_bf16_f32 v35, v46, v47
	s_nop 1
	v_mfma_f32_32x32x16_bf16 v[16:31], v[72:75], v[32:35], v[16:31]
	v_mfma_f32_32x32x16_bf16 v[0:15], v[76:79], v[32:35], v[0:15]
	v_add_f32_e32 v32, v48, v187
	v_add_f32_e32 v32, v49, v32
	v_add_f32_e32 v32, v50, v32
	v_add_f32_e32 v32, v51, v32
	v_add_f32_e32 v32, v52, v32
	v_add_f32_e32 v32, v53, v32
	v_add_f32_e32 v32, v54, v32
	v_add_f32_e32 v32, v55, v32
	v_add_f32_e32 v32, v56, v32
	v_add_f32_e32 v32, v57, v32
	v_add_f32_e32 v32, v58, v32
	v_add_f32_e32 v32, v59, v32
	v_add_f32_e32 v32, v60, v32
	v_add_f32_e32 v32, v61, v32
	v_add_f32_e32 v32, v62, v32
	v_add_f32_e32 v32, v63, v32
	v_add_f32_e32 v32, v96, v32
	v_add_f32_e32 v32, v97, v32
	v_add_f32_e32 v32, v98, v32
	v_add_f32_e32 v32, v99, v32
	v_add_f32_e32 v32, v36, v32
	v_add_f32_e32 v32, v37, v32
	v_add_f32_e32 v32, v38, v32
	v_add_f32_e32 v32, v39, v32
	v_add_f32_e32 v32, v40, v32
	v_add_f32_e32 v32, v41, v32
	v_add_f32_e32 v32, v42, v32
	v_add_f32_e32 v32, v43, v32
	v_add_f32_e32 v32, v44, v32
	v_add_f32_e32 v32, v45, v32
	v_add_f32_e32 v32, v46, v32
	v_add_f32_e32 v32, v47, v32
	ds_bpermute_b32 v33, v189, v32
	s_waitcnt lgkmcnt(0)
	v_add_f32_e32 v32, v32, v33
	v_rcp_f32_e32 v32, v32
	s_nop 0
	v_pk_mul_f32 v[16:17], v[16:17], v[32:33] op_sel_hi:[1,0]
	v_pk_mul_f32 v[18:19], v[18:19], v[32:33] op_sel_hi:[1,0]
	v_add_u32_e32 v33, v205, v206
	v_pk_mul_f32 v[0:1], v[0:1], v[32:33] op_sel_hi:[1,0]
	v_pk_mul_f32 v[2:3], v[2:3], v[32:33] op_sel_hi:[1,0]
	v_cvt_pk_bf16_f32 v16, v16, v17
	v_cvt_pk_bf16_f32 v17, v18, v19
	v_pk_mul_f32 v[18:19], v[20:21], v[32:33] op_sel_hi:[1,0]
	v_pk_mul_f32 v[20:21], v[22:23], v[32:33] op_sel_hi:[1,0]
	v_cvt_pk_bf16_f32 v0, v0, v1
	v_cvt_pk_bf16_f32 v1, v2, v3
	v_pk_mul_f32 v[2:3], v[4:5], v[32:33] op_sel_hi:[1,0]
	v_pk_mul_f32 v[4:5], v[6:7], v[32:33] op_sel_hi:[1,0]
	v_cvt_pk_bf16_f32 v18, v18, v19
	v_cvt_pk_bf16_f32 v19, v20, v21
	v_add_u32_e32 v22, 0xd000, v33
	v_cvt_pk_bf16_f32 v2, v2, v3
	v_cvt_pk_bf16_f32 v3, v4, v5
	ds_write2_b64 v22, v[16:17], v[18:19] offset1:2
	v_pk_mul_f32 v[16:17], v[24:25], v[32:33] op_sel_hi:[1,0]
	v_pk_mul_f32 v[18:19], v[26:27], v[32:33] op_sel_hi:[1,0]
	ds_write2_b64 v22, v[0:1], v[2:3] offset0:8 offset1:10
	v_pk_mul_f32 v[0:1], v[8:9], v[32:33] op_sel_hi:[1,0]
	v_pk_mul_f32 v[2:3], v[10:11], v[32:33] op_sel_hi:[1,0]
	v_cvt_pk_bf16_f32 v16, v16, v17
	v_cvt_pk_bf16_f32 v17, v18, v19
	v_pk_mul_f32 v[18:19], v[28:29], v[32:33] op_sel_hi:[1,0]
	v_pk_mul_f32 v[20:21], v[30:31], v[32:33] op_sel_hi:[1,0]
	v_cvt_pk_bf16_f32 v0, v0, v1
	v_cvt_pk_bf16_f32 v1, v2, v3
	v_pk_mul_f32 v[2:3], v[12:13], v[32:33] op_sel_hi:[1,0]
	v_pk_mul_f32 v[4:5], v[14:15], v[32:33] op_sel_hi:[1,0]
	v_cvt_pk_bf16_f32 v18, v18, v19
	v_cvt_pk_bf16_f32 v19, v20, v21
	v_cvt_pk_bf16_f32 v2, v2, v3
	v_cvt_pk_bf16_f32 v3, v4, v5
	ds_write2_b64 v22, v[16:17], v[18:19] offset0:4 offset1:6
	ds_write2_b64 v22, v[0:1], v[2:3] offset0:12 offset1:14
	s_waitcnt lgkmcnt(0)
	v_add_u32_e32 v0, v207, v208
	ds_read_b128 v[12:15], v0 offset:53248
	ds_read_b128 v[8:11], v0 offset:53264
	ds_read_b128 v[4:7], v0 offset:53280
	ds_read_b128 v[0:3], v0 offset:53296
	v_lshlrev_b32_e32 v20, 1, v180
	s_cbranch_vccnz .LBB0_1237
; DI unsigned cvtpk(float lo, float hi) { f32x2_t v = {lo, hi}; bf16x2_t b = __builtin_convertvector(v, bf16x2_t); return __builtin_bit_cast(unsigned, b); }
; DI float bflo(unsigned w) { return __uint_as_float(w << 16); }
; DI float bfhi(unsigned w) { return __uint_as_float(w & 0xffff0000u); }
; DI void attn_store(const f32x16 (&o)[2], float inv, bf16_t* d0, int dstride, const bf16_t* g0, int gstride, int lane, LAS unsigned char* stage) {
;     ...
;     if (g0) {
;         const bf16_t* gp = g0 + (size_t)row * gstride + half * 32;
; #pragma unroll
;         for (int i = 0; i < 4; ++i) {
;             const u32x4 z = gld16(gp + 8 * i);
; #pragma unroll
;             for (int k = 0; k < 4; ++k) v[i][k] = cvtpk(bflo(v[i][k]) * bflo(z[k]), bfhi(v[i][k]) * bfhi(z[k]));
;         }
;     }
;     bf16_t* dp = d0 + (size_t)row * dstride + half * 32;
; #pragma unroll
;     for (int i = 0; i < 4; ++i) *(u32x4*)(dp + 8 * i) = v[i];
;     asm volatile("s_waitcnt lgkmcnt(0)" ::: "memory");
	s_lshl_b64 s[12:13], s[16:17], 11
	s_add_u32 s5, s65, s12
	s_addc_u32 s13, s74, s13
	s_lshl_b32 s12, s4, 1
	s_add_u32 s12, s5, s12
	s_addc_u32 s13, s13, 0
	v_lshlrev_b32_e32 v144, 1, v184
	v_lshl_add_u64 v[16:17], s[12:13], 0, v[144:145]
	v_mov_b32_e32 v21, v145
	v_lshl_add_u64 v[16:17], v[16:17], 0, v[20:21]
	global_load_dwordx4 v[218:221], v[16:17], off
	global_load_dwordx4 v[222:225], v[16:17], off offset:16
	global_load_dwordx4 v[226:229], v[16:17], off offset:32
	global_load_dwordx4 v[230:233], v[16:17], off offset:48
	s_waitcnt lgkmcnt(3)
	v_lshlrev_b32_e32 v18, 16, v12
	v_and_b32_e32 v19, 0xffff0000, v12
	s_waitcnt vmcnt(3)
	v_mov_b32_e32 v22, v218
	v_mov_b32_e32 v23, v219
	v_mov_b32_e32 v24, v220
	v_mov_b32_e32 v25, v221
	v_lshlrev_b32_e32 v26, 16, v22
	v_and_b32_e32 v27, 0xffff0000, v22
	v_pk_mul_f32 v[18:19], v[18:19], v[26:27]
	v_lshlrev_b32_e32 v22, 16, v23
	v_cvt_pk_bf16_f32 v12, v18, v19
	v_lshlrev_b32_e32 v18, 16, v13
	v_and_b32_e32 v19, 0xffff0000, v13
	v_and_b32_e32 v23, 0xffff0000, v23
	v_pk_mul_f32 v[18:19], v[18:19], v[22:23]
	v_lshlrev_b32_e32 v22, 16, v24
	v_cvt_pk_bf16_f32 v13, v18, v19
	v_lshlrev_b32_e32 v18, 16, v14
	v_and_b32_e32 v19, 0xffff0000, v14
	v_and_b32_e32 v23, 0xffff0000, v24
	v_pk_mul_f32 v[18:19], v[18:19], v[22:23]
	v_lshlrev_b32_e32 v22, 16, v25
	v_cvt_pk_bf16_f32 v14, v18, v19
	v_lshlrev_b32_e32 v18, 16, v15
	v_and_b32_e32 v19, 0xffff0000, v15
	v_and_b32_e32 v23, 0xffff0000, v25
	v_pk_mul_f32 v[18:19], v[18:19], v[22:23]
	v_cvt_pk_bf16_f32 v15, v18, v19
	s_waitcnt lgkmcnt(2)
	v_lshlrev_b32_e32 v18, 16, v8
	v_and_b32_e32 v19, 0xffff0000, v8
	s_waitcnt vmcnt(2)
	v_mov_b32_e32 v22, v222
	v_mov_b32_e32 v23, v223
	v_mov_b32_e32 v24, v224
	v_mov_b32_e32 v25, v225
	v_lshlrev_b32_e32 v26, 16, v22
	v_and_b32_e32 v27, 0xffff0000, v22
	v_pk_mul_f32 v[18:19], v[18:19], v[26:27]
	v_lshlrev_b32_e32 v22, 16, v23
	v_cvt_pk_bf16_f32 v8, v18, v19
	v_lshlrev_b32_e32 v18, 16, v9
	v_and_b32_e32 v19, 0xffff0000, v9
	v_and_b32_e32 v23, 0xffff0000, v23
	v_pk_mul_f32 v[18:19], v[18:19], v[22:23]
	v_lshlrev_b32_e32 v22, 16, v24
	v_cvt_pk_bf16_f32 v9, v18, v19
	v_lshlrev_b32_e32 v18, 16, v10
	v_and_b32_e32 v19, 0xffff0000, v10
	v_and_b32_e32 v23, 0xffff0000, v24
	v_pk_mul_f32 v[18:19], v[18:19], v[22:23]
	v_lshlrev_b32_e32 v22, 16, v25
	v_cvt_pk_bf16_f32 v10, v18, v19
	v_lshlrev_b32_e32 v18, 16, v11
	v_and_b32_e32 v19, 0xffff0000, v11
	v_and_b32_e32 v23, 0xffff0000, v25
	v_pk_mul_f32 v[18:19], v[18:19], v[22:23]
	v_cvt_pk_bf16_f32 v11, v18, v19
	s_waitcnt lgkmcnt(1)
	v_lshlrev_b32_e32 v18, 16, v4
	v_and_b32_e32 v19, 0xffff0000, v4
	s_waitcnt vmcnt(1)
	v_mov_b32_e32 v22, v226
	v_mov_b32_e32 v23, v227
	v_mov_b32_e32 v24, v228
	v_mov_b32_e32 v25, v229
	v_lshlrev_b32_e32 v26, 16, v22
	v_and_b32_e32 v27, 0xffff0000, v22
	v_pk_mul_f32 v[18:19], v[18:19], v[26:27]
	v_lshlrev_b32_e32 v22, 16, v23
	v_cvt_pk_bf16_f32 v4, v18, v19
	v_lshlrev_b32_e32 v18, 16, v5
	v_and_b32_e32 v19, 0xffff0000, v5
	v_and_b32_e32 v23, 0xffff0000, v23
	v_pk_mul_f32 v[18:19], v[18:19], v[22:23]
	v_lshlrev_b32_e32 v22, 16, v24
	v_cvt_pk_bf16_f32 v5, v18, v19
	v_lshlrev_b32_e32 v18, 16, v6
	v_and_b32_e32 v19, 0xffff0000, v6
	v_and_b32_e32 v23, 0xffff0000, v24
	v_pk_mul_f32 v[18:19], v[18:19], v[22:23]
	v_lshlrev_b32_e32 v22, 16, v25
	v_cvt_pk_bf16_f32 v6, v18, v19
	v_lshlrev_b32_e32 v18, 16, v7
	v_and_b32_e32 v19, 0xffff0000, v7
	v_and_b32_e32 v23, 0xffff0000, v25
	v_pk_mul_f32 v[18:19], v[18:19], v[22:23]
	s_waitcnt lgkmcnt(0)
	v_lshlrev_b32_e32 v22, 16, v0
	v_cvt_pk_bf16_f32 v7, v18, v19
	v_and_b32_e32 v23, 0xffff0000, v0
	s_waitcnt vmcnt(0)
	v_mov_b32_e32 v16, v230
	v_mov_b32_e32 v17, v231
	v_mov_b32_e32 v18, v232
	v_mov_b32_e32 v19, v233
	v_lshlrev_b32_e32 v24, 16, v16
	v_and_b32_e32 v25, 0xffff0000, v16
	v_pk_mul_f32 v[22:23], v[22:23], v[24:25]
	v_lshlrev_b32_e32 v16, 16, v17
	v_cvt_pk_bf16_f32 v0, v22, v23
	v_lshlrev_b32_e32 v22, 16, v1
	v_and_b32_e32 v23, 0xffff0000, v1
	v_and_b32_e32 v17, 0xffff0000, v17
	v_pk_mul_f32 v[16:17], v[22:23], v[16:17]
	v_lshlrev_b32_e32 v22, 16, v18
	v_cvt_pk_bf16_f32 v1, v16, v17
	v_lshlrev_b32_e32 v16, 16, v2
	v_and_b32_e32 v17, 0xffff0000, v2
	v_and_b32_e32 v23, 0xffff0000, v18
	v_pk_mul_f32 v[16:17], v[16:17], v[22:23]
	v_lshlrev_b32_e32 v18, 16, v19
	v_cvt_pk_bf16_f32 v2, v16, v17
	v_lshlrev_b32_e32 v16, 16, v3
	v_and_b32_e32 v17, 0xffff0000, v3
	v_and_b32_e32 v19, 0xffff0000, v19
	v_pk_mul_f32 v[16:17], v[16:17], v[18:19]
	s_nop 0
	v_cvt_pk_bf16_f32 v3, v16, v17
	s_branch .LBB0_1237
